# v92 + zero-SrcC peeled first phases also in the single-tile loops (post1, post2, ph_out)
# baseline (speedup 1.0000x reference)
; template <class Epi>
; DI void gemm_phase(LAS unsigned char* lds, const Gemm g, const StaticOrder& S, const Epi& E) {
;     ...
;         const bool has_next = S.next(ui + 1, nxt);
;         const char* nA = has_next ? (const char*)g.A + (size_t)nxt.pm * tstep : cA; const char* nB = has_next ? (const char*)g.Bt + (size_t)nxt.pn * tstep : cB;
;         for (int t = 0; t < nt; t += 2) {
;             const bool last = (t == nt - 2);
;             const char* a1 = cA + (size_t)(t + 1) * kstep;
;             const char* a2 = last ? nA : cA + (size_t)(t + 2) * kstep; const char* b2 = last ? nB : cB + (size_t)(t + 2) * kstep;
;             const char* a3 = a2 + kstep; const char* b3 = b2 + kstep;
.LBB0_514:
	s_ashr_i32 s57, s56, 31
	s_lshl_b64 s[22:23], s[56:57], 19
	s_add_u32 s58, s72, s22
	s_addc_u32 s59, s73, s23
	s_and_b64 s[22:23], s[4:5], exec
	s_cselect_b32 s22, s59, s67
	s_cselect_b32 s23, s58, s66
	s_ashr_i32 s55, s54, 31
	s_lshl_b64 s[42:43], s[54:55], 19
	s_add_u32 s60, s95, s42
	s_addc_u32 s61, s30, s43
	s_and_b64 s[42:43], s[4:5], exec
	s_cselect_b32 s42, s61, s65
	s_cselect_b32 s43, s60, s64
	s_add_u32 s55, s64, 0x100
	s_addc_u32 s57, s65, 0
	s_add_u32 s64, s66, 0x40080
	s_addc_u32 s65, s67, 0
	s_mov_b32 s63, -2
	v_readfirstlane_b32 s101, v242
	s_nop 3
	s_lshr_b32 s101, s101, 8
	s_cmp_eq_u32 s101, 0
	s_cbranch_scc0 .Lsp_4
	s_setprio 1
; #define PG8_STAGE(bufoff, gbase, voff) do { _Pragma("unroll") for (int _i = 0; _i < 2; ++_i) \
;         __builtin_amdgcn_global_load_lds((const unsigned*)((const char*)(gbase) + (voff)[_i]), (LAS unsigned*)(lds + (bufoff) + ldsw + _i * 8192), 16, 0, 0); } while (0)
; #define PG8_LDA(dst, b, h) do { _Pragma("unroll") for (int m = 0; m < 4; ++m) _Pragma("unroll") for (int k = 0; k < 2; ++k) dst[m][k] = *(const LAS bf16x8*)(lds + PG8_SA(b, h) + aoff + m * 2048 + k * 1024); } while (0)
; #define PG8_LDB(dst, b, h) do { _Pragma("unroll") for (int n = 0; n < 2; ++n) _Pragma("unroll") for (int k = 0; k < 2; ++k) dst[n][k] = *(const LAS bf16x8*)(lds + PG8_SB(b, h) + boff + n * 2048 + k * 1024); } while (0)
; #define PG8_MMA(ai, bj, At, Bt) do { __builtin_amdgcn_s_setprio(1); _Pragma("unroll") for (int m = 0; m < 4; ++m) _Pragma("unroll") for (int n = 0; n < 2; ++n) _Pragma("unroll") for (int k = 0; k < 2; ++k) \
;         acc[ai][bj][m][n] = __builtin_amdgcn_mfma_f32_16x16x32_bf16(Bt[n][k], At[m][k], acc[ai][bj][m][n], 0, 0, 0); __builtin_amdgcn_s_setprio(0); } while (0)
; #define PG8_WAIT_V(n) asm volatile("s_waitcnt vmcnt(" #n ")" ::: "memory")
; #define PG8_WAIT_L(n) asm volatile("s_waitcnt lgkmcnt(" #n ")" ::: "memory")
; #define PG8_BAR __builtin_amdgcn_s_barrier()
; #define PG8_SCHED __builtin_amdgcn_sched_barrier(0)
; template <class Epi>
; DI void gemm_phase(LAS unsigned char* lds, const Gemm g, const StaticOrder& S, const Epi& E) {
;     ...
;             PG8_LDB(B0, 0, 0); PG8_LDB(B1, 0, 1); PG8_SCHED; PG8_LDA(At, 0, 0); PG8_STAGE(PG8_SA(1, 1), a1 + hstep, voffA);
;             PG8_WAIT_V(8); PG8_WAIT_L(0); PG8_BAR; PG8_MMA(0, 0, At, B0); PG8_MMA(0, 1, At, B1); PG8_BAR; PG8_SCHED;
;             PG8_LDA(At, 0, 1); PG8_STAGE(PG8_SB(0, 0), b2, voffB); PG8_STAGE(PG8_SB(0, 1), b2 + hstep, voffB); PG8_STAGE(PG8_SA(0, 0), a2, voffA);
;             PG8_WAIT_V(8); PG8_WAIT_L(0); PG8_BAR; PG8_MMA(1, 0, At, B0); PG8_MMA(1, 1, At, B1); PG8_BAR; PG8_SCHED;
.Lsp_4:
	s_add_u32 s18, s64, 0xfffc0080
	s_addc_u32 s19, s65, -1
	s_add_i32 s91, 0, 0x10000
	s_cmp_eq_u32 s63, 12
	s_cselect_b32 s69, s22, s19
	s_cselect_b32 s68, s23, s18
	s_cselect_b32 s67, s42, s57
	s_cselect_b32 s66, s43, s55
	s_add_i32 s18, 0, 0x14000
	v_add_u32_e32 v62, s91, v180
	v_add_u32_e32 v170, s18, v180
	ds_read_b128 v[42:45], v62
	ds_read_b128 v[46:49], v62 offset:1024
	ds_read_b128 v[58:61], v62 offset:2048
	ds_read_b128 v[62:65], v62 offset:3072
	ds_read_b128 v[138:141], v170
	ds_read_b128 v[142:145], v170 offset:1024
	ds_read_b128 v[154:157], v170 offset:2048
	ds_read_b128 v[170:173], v170 offset:3072
	v_lshl_add_u64 v[178:179], s[64:65], 0, v[168:169]
	s_add_i32 m0, s94, 0xc000
	ds_read_b128 v[174:177], v182
	ds_read_b128 v[184:187], v182 offset:1024
	ds_read_b128 v[188:191], v182 offset:2048
	ds_read_b128 v[200:203], v182 offset:3072
	ds_read_b128 v[206:209], v182 offset:4096
	ds_read_b128 v[210:213], v182 offset:5120
	ds_read_b128 v[214:217], v182 offset:6144
	ds_read_b128 v[218:221], v182 offset:7168
	global_load_lds_dwordx4 v[178:179], off
	v_lshl_add_u64 v[178:179], s[64:65], 0, v[166:167]
	s_add_i32 m0, s94, 0xe000
	s_nop 0
	global_load_lds_dwordx4 v[178:179], off
	s_waitcnt vmcnt(8)
	s_waitcnt lgkmcnt(0)
	s_barrier
	s_waitcnt lgkmcnt(0)
	v_mfma_f32_16x16x32_bf16 v[150:153], v[42:45], v[174:177], 0
	v_mfma_f32_16x16x32_bf16 v[146:149], v[58:61], v[174:177], 0
	v_mfma_f32_16x16x32_bf16 v[126:129], v[42:45], v[188:191], 0
	v_mfma_f32_16x16x32_bf16 v[122:125], v[58:61], v[188:191], 0
	v_mfma_f32_16x16x32_bf16 v[110:113], v[42:45], v[206:209], 0
	v_mfma_f32_16x16x32_bf16 v[106:109], v[58:61], v[206:209], 0
	v_mfma_f32_16x16x32_bf16 v[94:97], v[42:45], v[214:217], 0
	v_mfma_f32_16x16x32_bf16 v[90:93], v[58:61], v[214:217], 0
	v_mfma_f32_16x16x32_bf16 v[150:153], v[46:49], v[184:187], v[150:153]
	v_mfma_f32_16x16x32_bf16 v[146:149], v[62:65], v[184:187], v[146:149]
	v_mfma_f32_16x16x32_bf16 v[126:129], v[46:49], v[200:203], v[126:129]
	v_mfma_f32_16x16x32_bf16 v[122:125], v[62:65], v[200:203], v[122:125]
	v_mfma_f32_16x16x32_bf16 v[110:113], v[46:49], v[210:213], v[110:113]
	v_mfma_f32_16x16x32_bf16 v[106:109], v[62:65], v[210:213], v[106:109]
	v_mfma_f32_16x16x32_bf16 v[94:97], v[46:49], v[218:221], v[94:97]
	v_mfma_f32_16x16x32_bf16 v[90:93], v[62:65], v[218:221], v[90:93]
	v_mfma_f32_16x16x32_bf16 v[134:137], v[138:141], v[174:177], 0
	v_mfma_f32_16x16x32_bf16 v[130:133], v[154:157], v[174:177], 0
	v_mfma_f32_16x16x32_bf16 v[118:121], v[138:141], v[188:191], 0
	v_mfma_f32_16x16x32_bf16 v[114:117], v[154:157], v[188:191], 0
	v_mfma_f32_16x16x32_bf16 v[102:105], v[138:141], v[206:209], 0
	v_mfma_f32_16x16x32_bf16 v[98:101], v[154:157], v[206:209], 0
	v_mfma_f32_16x16x32_bf16 v[86:89], v[138:141], v[214:217], 0
	v_mfma_f32_16x16x32_bf16 v[82:85], v[154:157], v[214:217], 0
	v_mfma_f32_16x16x32_bf16 v[134:137], v[142:145], v[184:187], v[134:137]
	v_mfma_f32_16x16x32_bf16 v[130:133], v[170:173], v[184:187], v[130:133]
	v_mfma_f32_16x16x32_bf16 v[118:121], v[142:145], v[200:203], v[118:121]
	v_mfma_f32_16x16x32_bf16 v[114:117], v[170:173], v[200:203], v[114:117]
	v_mfma_f32_16x16x32_bf16 v[102:105], v[142:145], v[210:213], v[102:105]
	v_mfma_f32_16x16x32_bf16 v[98:101], v[170:173], v[210:213], v[98:101]
	v_mfma_f32_16x16x32_bf16 v[86:89], v[142:145], v[218:221], v[86:89]
	v_mfma_f32_16x16x32_bf16 v[82:85], v[170:173], v[218:221], v[82:85]
	s_barrier
	s_add_i32 s19, s91, s31
	v_lshl_add_u64 v[178:179], s[66:67], 0, v[160:161]
	s_mov_b32 m0, s19
	ds_read_b128 v[174:177], v182 offset:16384
	ds_read_b128 v[184:187], v182 offset:17408
	ds_read_b128 v[188:191], v182 offset:18432
	ds_read_b128 v[200:203], v182 offset:19456
	ds_read_b128 v[206:209], v182 offset:20480
	ds_read_b128 v[210:213], v182 offset:21504
	ds_read_b128 v[214:217], v182 offset:22528
	ds_read_b128 v[218:221], v182 offset:23552
	global_load_lds_dwordx4 v[178:179], off
	s_add_i32 m0, s19, 0x2000
	s_add_u32 vcc_lo, s66, 0x40000
	v_lshl_add_u64 v[192:193], s[66:67], 0, v[164:165]
	s_addc_u32 vcc_hi, s67, 0
	s_add_i32 s18, s18, s31
	global_load_lds_dwordx4 v[192:193], off
	v_lshl_add_u64 v[204:205], vcc, 0, v[160:161]
	s_mov_b32 m0, s18
	v_lshl_add_u64 v[222:223], s[68:69], 0, v[162:163]
	global_load_lds_dwordx4 v[204:205], off
	v_lshl_add_u64 v[204:205], vcc, 0, v[164:165]
	s_add_i32 m0, s18, 0x2000
	s_nop 0
	global_load_lds_dwordx4 v[204:205], off
	v_lshl_add_u64 v[204:205], s[68:69], 0, v[158:159]
	s_mov_b32 m0, s94
	s_nop 0
	global_load_lds_dwordx4 v[204:205], off
	s_mov_b32 m0, s93
	s_nop 0
	global_load_lds_dwordx4 v[222:223], off
	s_waitcnt vmcnt(8)
	s_waitcnt lgkmcnt(0)
	s_barrier
	s_waitcnt lgkmcnt(0)
	v_mfma_f32_16x16x32_bf16 v[78:81], v[42:45], v[174:177], 0
	v_mfma_f32_16x16x32_bf16 v[74:77], v[58:61], v[174:177], 0
	v_mfma_f32_16x16x32_bf16 v[54:57], v[42:45], v[188:191], 0
	v_mfma_f32_16x16x32_bf16 v[50:53], v[58:61], v[188:191], 0
	v_mfma_f32_16x16x32_bf16 v[30:33], v[42:45], v[206:209], 0
	v_mfma_f32_16x16x32_bf16 v[26:29], v[58:61], v[206:209], 0
	v_mfma_f32_16x16x32_bf16 v[14:17], v[42:45], v[214:217], 0
	v_mfma_f32_16x16x32_bf16 v[10:13], v[58:61], v[214:217], 0
	v_mfma_f32_16x16x32_bf16 v[78:81], v[46:49], v[184:187], v[78:81]
	v_mfma_f32_16x16x32_bf16 v[74:77], v[62:65], v[184:187], v[74:77]
	v_mfma_f32_16x16x32_bf16 v[54:57], v[46:49], v[200:203], v[54:57]
	v_mfma_f32_16x16x32_bf16 v[50:53], v[62:65], v[200:203], v[50:53]
	v_mfma_f32_16x16x32_bf16 v[30:33], v[46:49], v[210:213], v[30:33]
	v_mfma_f32_16x16x32_bf16 v[26:29], v[62:65], v[210:213], v[26:29]
	v_mfma_f32_16x16x32_bf16 v[14:17], v[46:49], v[218:221], v[14:17]
	v_mfma_f32_16x16x32_bf16 v[10:13], v[62:65], v[218:221], v[10:13]
	v_mfma_f32_16x16x32_bf16 v[38:41], v[138:141], v[188:191], 0
	v_mfma_f32_16x16x32_bf16 v[34:37], v[154:157], v[188:191], 0
	v_mfma_f32_16x16x32_bf16 v[22:25], v[138:141], v[206:209], 0
	v_mfma_f32_16x16x32_bf16 v[18:21], v[154:157], v[206:209], 0
	v_mfma_f32_16x16x32_bf16 v[6:9], v[138:141], v[214:217], 0
	v_mfma_f32_16x16x32_bf16 v[2:5], v[154:157], v[214:217], 0
	v_mfma_f32_16x16x32_bf16 v[42:45], v[138:141], v[174:177], 0
	v_mfma_f32_16x16x32_bf16 v[46:49], v[154:157], v[174:177], 0
	v_mfma_f32_16x16x32_bf16 v[38:41], v[142:145], v[200:203], v[38:41]
	v_mfma_f32_16x16x32_bf16 v[34:37], v[170:173], v[200:203], v[34:37]
	v_mfma_f32_16x16x32_bf16 v[22:25], v[142:145], v[210:213], v[22:25]
	v_mfma_f32_16x16x32_bf16 v[18:21], v[170:173], v[210:213], v[18:21]
	v_mfma_f32_16x16x32_bf16 v[6:9], v[142:145], v[218:221], v[6:9]
	v_mfma_f32_16x16x32_bf16 v[2:5], v[170:173], v[218:221], v[2:5]
	v_mfma_f32_16x16x32_bf16 v[42:45], v[142:145], v[184:187], v[42:45]
	v_mfma_f32_16x16x32_bf16 v[46:49], v[170:173], v[184:187], v[46:49]
	s_barrier
	s_branch .Lp3_post1

; #define PG8_STAGE(bufoff, gbase, voff) do { _Pragma("unroll") for (int _i = 0; _i < 2; ++_i) \
;         __builtin_amdgcn_global_load_lds((const unsigned*)((const char*)(gbase) + (voff)[_i]), (LAS unsigned*)(lds + (bufoff) + ldsw + _i * 8192), 16, 0, 0); } while (0)
; #define PG8_LDA(dst, b, h) do { _Pragma("unroll") for (int m = 0; m < 4; ++m) _Pragma("unroll") for (int k = 0; k < 2; ++k) dst[m][k] = *(const LAS bf16x8*)(lds + PG8_SA(b, h) + aoff + m * 2048 + k * 1024); } while (0)
; #define PG8_LDB(dst, b, h) do { _Pragma("unroll") for (int n = 0; n < 2; ++n) _Pragma("unroll") for (int k = 0; k < 2; ++k) dst[n][k] = *(const LAS bf16x8*)(lds + PG8_SB(b, h) + boff + n * 2048 + k * 1024); } while (0)
; #define PG8_MMA(ai, bj, At, Bt) do { __builtin_amdgcn_s_setprio(1); _Pragma("unroll") for (int m = 0; m < 4; ++m) _Pragma("unroll") for (int n = 0; n < 2; ++n) _Pragma("unroll") for (int k = 0; k < 2; ++k) \
;         acc[ai][bj][m][n] = __builtin_amdgcn_mfma_f32_16x16x32_bf16(Bt[n][k], At[m][k], acc[ai][bj][m][n], 0, 0, 0); __builtin_amdgcn_s_setprio(0); } while (0)
; #define PG8_WAIT_V(n) asm volatile("s_waitcnt vmcnt(" #n ")" ::: "memory")
; #define PG8_WAIT_L(n) asm volatile("s_waitcnt lgkmcnt(" #n ")" ::: "memory")
; #define PG8_BAR __builtin_amdgcn_s_barrier()
; #define PG8_SCHED __builtin_amdgcn_sched_barrier(0)
; template <class Epi>
; DI void gemm_phase(LAS unsigned char* lds, const Gemm g, const StaticOrder& S, const Epi& E) {
;     ...
;             PG8_LDB(B0, 1, 0); PG8_LDB(B1, 1, 1); PG8_SCHED; PG8_LDA(At, 1, 0); PG8_STAGE(PG8_SA(0, 1), a2 + hstep, voffA);
;             PG8_WAIT_V(8); PG8_WAIT_L(0); PG8_BAR; PG8_MMA(0, 0, At, B0); PG8_MMA(0, 1, At, B1); PG8_BAR; PG8_SCHED;
.Lp3_post1:
	s_add_i32 s18, 0, 0x18000
	s_add_i32 s19, 0, 0x1c000
	v_add_u32_e32 v70, s18, v180
	v_add_u32_e32 v170, s19, v180
	ds_read_b128 v[58:61], v70
	ds_read_b128 v[62:65], v70 offset:1024
	ds_read_b128 v[66:69], v70 offset:2048
	ds_read_b128 v[70:73], v70 offset:3072
	ds_read_b128 v[138:141], v170
	ds_read_b128 v[142:145], v170 offset:1024
	ds_read_b128 v[154:157], v170 offset:2048
	ds_read_b128 v[170:173], v170 offset:3072
	s_add_u32 s68, s68, 0x40000
	s_addc_u32 s69, s69, 0
	s_mov_b32 m0, s36
	v_lshl_add_u64 v[224:225], s[68:69], 0, v[158:159]
	ds_read_b128 v[174:177], v182 offset:32768
	ds_read_b128 v[184:187], v182 offset:33792
	ds_read_b128 v[188:191], v182 offset:34816
	ds_read_b128 v[200:203], v182 offset:35840
	ds_read_b128 v[206:209], v182 offset:36864
	ds_read_b128 v[210:213], v182 offset:37888
	ds_read_b128 v[214:217], v182 offset:38912
	ds_read_b128 v[218:221], v182 offset:39936
	global_load_lds_dwordx4 v[224:225], off
	v_lshl_add_u64 v[224:225], s[68:69], 0, v[162:163]
	s_mov_b32 m0, s37
	s_nop 0
	global_load_lds_dwordx4 v[224:225], off
	s_waitcnt vmcnt(8)
	s_waitcnt lgkmcnt(0)
	s_barrier
	s_waitcnt lgkmcnt(0)
	v_mfma_f32_16x16x32_bf16 v[150:153], v[58:61], v[174:177], v[150:153]
	v_mfma_f32_16x16x32_bf16 v[146:149], v[66:69], v[174:177], v[146:149]
	v_mfma_f32_16x16x32_bf16 v[126:129], v[58:61], v[188:191], v[126:129]
	v_mfma_f32_16x16x32_bf16 v[122:125], v[66:69], v[188:191], v[122:125]
	v_mfma_f32_16x16x32_bf16 v[110:113], v[58:61], v[206:209], v[110:113]
	v_mfma_f32_16x16x32_bf16 v[106:109], v[66:69], v[206:209], v[106:109]
	v_mfma_f32_16x16x32_bf16 v[94:97], v[58:61], v[214:217], v[94:97]
	v_mfma_f32_16x16x32_bf16 v[90:93], v[66:69], v[214:217], v[90:93]
	v_mfma_f32_16x16x32_bf16 v[150:153], v[62:65], v[184:187], v[150:153]
	v_mfma_f32_16x16x32_bf16 v[146:149], v[70:73], v[184:187], v[146:149]
	v_mfma_f32_16x16x32_bf16 v[126:129], v[62:65], v[200:203], v[126:129]
	v_mfma_f32_16x16x32_bf16 v[122:125], v[70:73], v[200:203], v[122:125]
	v_mfma_f32_16x16x32_bf16 v[110:113], v[62:65], v[210:213], v[110:113]
	v_mfma_f32_16x16x32_bf16 v[106:109], v[70:73], v[210:213], v[106:109]
	v_mfma_f32_16x16x32_bf16 v[94:97], v[62:65], v[218:221], v[94:97]
	v_mfma_f32_16x16x32_bf16 v[90:93], v[70:73], v[218:221], v[90:93]
	v_mfma_f32_16x16x32_bf16 v[134:137], v[138:141], v[174:177], v[134:137]
	v_mfma_f32_16x16x32_bf16 v[130:133], v[154:157], v[174:177], v[130:133]
	v_mfma_f32_16x16x32_bf16 v[118:121], v[138:141], v[188:191], v[118:121]
	v_mfma_f32_16x16x32_bf16 v[114:117], v[154:157], v[188:191], v[114:117]
	v_mfma_f32_16x16x32_bf16 v[102:105], v[138:141], v[206:209], v[102:105]
	v_mfma_f32_16x16x32_bf16 v[98:101], v[154:157], v[206:209], v[98:101]
	v_mfma_f32_16x16x32_bf16 v[86:89], v[138:141], v[214:217], v[86:89]
	v_mfma_f32_16x16x32_bf16 v[82:85], v[154:157], v[214:217], v[82:85]
	v_mfma_f32_16x16x32_bf16 v[134:137], v[142:145], v[184:187], v[134:137]
	v_mfma_f32_16x16x32_bf16 v[130:133], v[170:173], v[184:187], v[130:133]
	v_mfma_f32_16x16x32_bf16 v[118:121], v[142:145], v[200:203], v[118:121]
	v_mfma_f32_16x16x32_bf16 v[114:117], v[170:173], v[200:203], v[114:117]
	v_mfma_f32_16x16x32_bf16 v[102:105], v[142:145], v[210:213], v[102:105]
	v_mfma_f32_16x16x32_bf16 v[98:101], v[170:173], v[210:213], v[98:101]
	v_mfma_f32_16x16x32_bf16 v[86:89], v[142:145], v[218:221], v[86:89]
	v_mfma_f32_16x16x32_bf16 v[82:85], v[170:173], v[218:221], v[82:85]
	s_barrier
; #define PG8_STAGE(bufoff, gbase, voff) do { _Pragma("unroll") for (int _i = 0; _i < 2; ++_i) \
;         __builtin_amdgcn_global_load_lds((const unsigned*)((const char*)(gbase) + (voff)[_i]), (LAS unsigned*)(lds + (bufoff) + ldsw + _i * 8192), 16, 0, 0); } while (0)
; #define PG8_LDA(dst, b, h) do { _Pragma("unroll") for (int m = 0; m < 4; ++m) _Pragma("unroll") for (int k = 0; k < 2; ++k) dst[m][k] = *(const LAS bf16x8*)(lds + PG8_SA(b, h) + aoff + m * 2048 + k * 1024); } while (0)
; #define PG8_MMA(ai, bj, At, Bt) do { __builtin_amdgcn_s_setprio(1); _Pragma("unroll") for (int m = 0; m < 4; ++m) _Pragma("unroll") for (int n = 0; n < 2; ++n) _Pragma("unroll") for (int k = 0; k < 2; ++k) \
;         acc[ai][bj][m][n] = __builtin_amdgcn_mfma_f32_16x16x32_bf16(Bt[n][k], At[m][k], acc[ai][bj][m][n], 0, 0, 0); __builtin_amdgcn_s_setprio(0); } while (0)
; #define PG8_WAIT_V(n) asm volatile("s_waitcnt vmcnt(" #n ")" ::: "memory")
; #define PG8_WAIT_L(n) asm volatile("s_waitcnt lgkmcnt(" #n ")" ::: "memory")
; #define PG8_BAR __builtin_amdgcn_s_barrier()
; #define PG8_SCHED __builtin_amdgcn_sched_barrier(0)
; template <class Epi>
; DI void gemm_phase(LAS unsigned char* lds, const Gemm g, const StaticOrder& S, const Epi& E) {
;     ...
;             PG8_LDA(At, 1, 1); PG8_STAGE(PG8_SB(1, 0), b3, voffB); PG8_STAGE(PG8_SB(1, 1), b3 + hstep, voffB); PG8_STAGE(PG8_SA(1, 0), a3, voffA);
;             PG8_WAIT_V(8); PG8_WAIT_L(0); PG8_BAR; PG8_MMA(1, 0, At, B0); PG8_MMA(1, 1, At, B1); PG8_BAR; PG8_SCHED;
;         }
;         if (wr == 0) PG8_BAR;
	s_add_i32 s18, s18, s31
	v_lshl_add_u64 v[178:179], v[178:179], 0, s[20:21]
	s_mov_b32 m0, s18
	ds_read_b128 v[174:177], v182 offset:49152
	ds_read_b128 v[184:187], v182 offset:50176
	ds_read_b128 v[188:191], v182 offset:51200
	ds_read_b128 v[200:203], v182 offset:52224
	ds_read_b128 v[206:209], v182 offset:53248
	ds_read_b128 v[210:213], v182 offset:54272
	ds_read_b128 v[214:217], v182 offset:55296
	ds_read_b128 v[218:221], v182 offset:56320
	global_load_lds_dwordx4 v[178:179], off
	s_add_i32 m0, s18, 0x2000
	s_add_u32 s66, s66, 0x40080
	v_lshl_add_u64 v[178:179], v[192:193], 0, s[20:21]
	s_addc_u32 s67, s67, 0
	s_add_i32 s18, s19, s31
	global_load_lds_dwordx4 v[178:179], off
	v_lshl_add_u64 v[178:179], s[66:67], 0, v[160:161]
	s_mov_b32 m0, s18
	s_nop 0
	global_load_lds_dwordx4 v[178:179], off
	v_lshl_add_u64 v[178:179], s[66:67], 0, v[164:165]
	s_add_i32 m0, s18, 0x2000
	s_nop 0
	global_load_lds_dwordx4 v[178:179], off
	v_lshl_add_u64 v[178:179], v[204:205], 0, s[20:21]
	s_mov_b32 m0, s24
	s_nop 0
	global_load_lds_dwordx4 v[178:179], off
	v_lshl_add_u64 v[178:179], v[222:223], 0, s[20:21]
	s_mov_b32 m0, s25
	s_nop 0
	global_load_lds_dwordx4 v[178:179], off
	s_waitcnt vmcnt(8)
	s_waitcnt lgkmcnt(0)
	s_barrier
	s_waitcnt lgkmcnt(0)
	v_mfma_f32_16x16x32_bf16 v[78:81], v[58:61], v[174:177], v[78:81]
	v_mfma_f32_16x16x32_bf16 v[74:77], v[66:69], v[174:177], v[74:77]
	v_mfma_f32_16x16x32_bf16 v[54:57], v[58:61], v[188:191], v[54:57]
	v_mfma_f32_16x16x32_bf16 v[50:53], v[66:69], v[188:191], v[50:53]
	v_mfma_f32_16x16x32_bf16 v[30:33], v[58:61], v[206:209], v[30:33]
	v_mfma_f32_16x16x32_bf16 v[26:29], v[66:69], v[206:209], v[26:29]
	v_mfma_f32_16x16x32_bf16 v[14:17], v[58:61], v[214:217], v[14:17]
	v_mfma_f32_16x16x32_bf16 v[10:13], v[66:69], v[214:217], v[10:13]
	v_mfma_f32_16x16x32_bf16 v[78:81], v[62:65], v[184:187], v[78:81]
	v_mfma_f32_16x16x32_bf16 v[74:77], v[70:73], v[184:187], v[74:77]
	v_mfma_f32_16x16x32_bf16 v[54:57], v[62:65], v[200:203], v[54:57]
	v_mfma_f32_16x16x32_bf16 v[50:53], v[70:73], v[200:203], v[50:53]
	v_mfma_f32_16x16x32_bf16 v[30:33], v[62:65], v[210:213], v[30:33]
	v_mfma_f32_16x16x32_bf16 v[26:29], v[70:73], v[210:213], v[26:29]
	v_mfma_f32_16x16x32_bf16 v[14:17], v[62:65], v[218:221], v[14:17]
	v_mfma_f32_16x16x32_bf16 v[10:13], v[70:73], v[218:221], v[10:13]
	v_mfma_f32_16x16x32_bf16 v[42:45], v[138:141], v[174:177], v[42:45]
	v_mfma_f32_16x16x32_bf16 v[70:73], v[142:145], v[184:187], v[42:45]
	v_mfma_f32_16x16x32_bf16 v[42:45], v[154:157], v[174:177], v[46:49]
	v_mfma_f32_16x16x32_bf16 v[38:41], v[138:141], v[188:191], v[38:41]
	v_mfma_f32_16x16x32_bf16 v[34:37], v[154:157], v[188:191], v[34:37]
	v_mfma_f32_16x16x32_bf16 v[22:25], v[138:141], v[206:209], v[22:25]
	v_mfma_f32_16x16x32_bf16 v[18:21], v[154:157], v[206:209], v[18:21]
	v_mfma_f32_16x16x32_bf16 v[6:9], v[138:141], v[214:217], v[6:9]
	v_mfma_f32_16x16x32_bf16 v[2:5], v[154:157], v[214:217], v[2:5]
	v_mfma_f32_16x16x32_bf16 v[66:69], v[170:173], v[184:187], v[42:45]
	v_mfma_f32_16x16x32_bf16 v[38:41], v[142:145], v[200:203], v[38:41]
	v_mfma_f32_16x16x32_bf16 v[34:37], v[170:173], v[200:203], v[34:37]
	v_mfma_f32_16x16x32_bf16 v[22:25], v[142:145], v[210:213], v[22:25]
	v_mfma_f32_16x16x32_bf16 v[18:21], v[170:173], v[210:213], v[18:21]
	v_mfma_f32_16x16x32_bf16 v[6:9], v[142:145], v[218:221], v[6:9]
	v_mfma_f32_16x16x32_bf16 v[2:5], v[170:173], v[218:221], v[2:5]
	s_barrier
	s_add_i32 s63, s63, 2
	s_add_u32 s55, s55, 0x100
	s_addc_u32 s57, s57, 0
	s_add_u32 s64, s64, 0x100
	s_addc_u32 s65, s65, 0
	s_cmp_gt_u32 s63, 13
	s_cbranch_scc0 .LBB0_515
	s_setprio 0
	s_and_b64 vcc, exec, s[52:53]
	s_cbranch_vccz .LBB0_518
	s_barrier

; template <class Epi>
; DI void gemm_phase(LAS unsigned char* lds, const Gemm g, const StaticOrder& S, const Epi& E) {
;     ...
;         const bool has_next = S.next(ui + 1, nxt);
;         const char* nA = has_next ? (const char*)g.A + (size_t)nxt.pm * tstep : cA; const char* nB = has_next ? (const char*)g.Bt + (size_t)nxt.pn * tstep : cB;
;         for (int t = 0; t < nt; t += 2) {
;             const bool last = (t == nt - 2);
;             const char* a1 = cA + (size_t)(t + 1) * kstep;
;             const char* a2 = last ? nA : cA + (size_t)(t + 2) * kstep; const char* b2 = last ? nB : cB + (size_t)(t + 2) * kstep;
;             const char* a3 = a2 + kstep; const char* b3 = b2 + kstep;
.LBB0_538:
	s_ashr_i32 s59, s58, 31
	s_lshl_b64 s[60:61], s[58:59], 18
	s_add_u32 s60, s30, s60
	s_addc_u32 s61, s31, s61
	s_and_b64 s[62:63], s[4:5], exec
	s_cselect_b32 s23, s61, s69
	s_cselect_b32 s43, s60, s68
	s_ashr_i32 s57, s56, 31
	s_lshl_b64 s[62:63], s[56:57], 18
	s_add_u32 s62, s36, s62
	s_addc_u32 s63, s37, s63
	s_and_b64 s[70:71], s[4:5], exec
	s_cselect_b32 s57, s63, s67
	s_cselect_b32 s59, s62, s66
	s_add_u32 s94, s66, 0x100
	s_addc_u32 s95, s67, 0
	s_add_u32 s66, s68, 0x20080
	s_addc_u32 s67, s69, 0
	s_mov_b32 vcc_lo, -2
	v_readfirstlane_b32 s101, v242
	s_nop 3
	s_lshr_b32 s101, s101, 8
	s_cmp_eq_u32 s101, 0
	s_cbranch_scc0 .Lsp_3
	s_setprio 1
; #define PG8_STAGE(bufoff, gbase, voff) do { _Pragma("unroll") for (int _i = 0; _i < 2; ++_i) \
;         __builtin_amdgcn_global_load_lds((const unsigned*)((const char*)(gbase) + (voff)[_i]), (LAS unsigned*)(lds + (bufoff) + ldsw + _i * 8192), 16, 0, 0); } while (0)
; #define PG8_LDA(dst, b, h) do { _Pragma("unroll") for (int m = 0; m < 4; ++m) _Pragma("unroll") for (int k = 0; k < 2; ++k) dst[m][k] = *(const LAS bf16x8*)(lds + PG8_SA(b, h) + aoff + m * 2048 + k * 1024); } while (0)
; #define PG8_LDB(dst, b, h) do { _Pragma("unroll") for (int n = 0; n < 2; ++n) _Pragma("unroll") for (int k = 0; k < 2; ++k) dst[n][k] = *(const LAS bf16x8*)(lds + PG8_SB(b, h) + boff + n * 2048 + k * 1024); } while (0)
; #define PG8_MMA(ai, bj, At, Bt) do { __builtin_amdgcn_s_setprio(1); _Pragma("unroll") for (int m = 0; m < 4; ++m) _Pragma("unroll") for (int n = 0; n < 2; ++n) _Pragma("unroll") for (int k = 0; k < 2; ++k) \
;         acc[ai][bj][m][n] = __builtin_amdgcn_mfma_f32_16x16x32_bf16(Bt[n][k], At[m][k], acc[ai][bj][m][n], 0, 0, 0); __builtin_amdgcn_s_setprio(0); } while (0)
; #define PG8_WAIT_V(n) asm volatile("s_waitcnt vmcnt(" #n ")" ::: "memory")
; #define PG8_WAIT_L(n) asm volatile("s_waitcnt lgkmcnt(" #n ")" ::: "memory")
; #define PG8_BAR __builtin_amdgcn_s_barrier()
; #define PG8_SCHED __builtin_amdgcn_sched_barrier(0)
; template <class Epi>
; DI void gemm_phase(LAS unsigned char* lds, const Gemm g, const StaticOrder& S, const Epi& E) {
;     ...
;             PG8_LDB(B0, 0, 0); PG8_LDB(B1, 0, 1); PG8_SCHED; PG8_LDA(At, 0, 0); PG8_STAGE(PG8_SA(1, 1), a1 + hstep, voffA);
;             PG8_WAIT_V(8); PG8_WAIT_L(0); PG8_BAR; PG8_MMA(0, 0, At, B0); PG8_MMA(0, 1, At, B1); PG8_BAR; PG8_SCHED;
;             PG8_LDA(At, 0, 1); PG8_STAGE(PG8_SB(0, 0), b2, voffB); PG8_STAGE(PG8_SB(0, 1), b2 + hstep, voffB); PG8_STAGE(PG8_SA(0, 0), a2, voffA);
;             PG8_WAIT_V(8); PG8_WAIT_L(0); PG8_BAR; PG8_MMA(1, 0, At, B0); PG8_MMA(1, 1, At, B1); PG8_BAR; PG8_SCHED;
.Lsp_3:
	s_add_u32 s18, s66, 0xfffe0080
	s_addc_u32 s19, s67, -1
	s_add_i32 vcc_hi, 0, 0x10000
	s_cmp_eq_u32 vcc_lo, 4
	s_cselect_b32 s71, s23, s19
	s_cselect_b32 s70, s43, s18
	s_cselect_b32 s69, s57, s95
	s_cselect_b32 s68, s59, s94
	s_add_i32 s81, 0, 0x14000
	v_add_u32_e32 v86, vcc_hi, v182
	v_add_u32_e32 v158, s81, v182
	ds_read_b128 v[66:69], v86
	ds_read_b128 v[70:73], v86 offset:1024
	ds_read_b128 v[82:85], v86 offset:2048
	ds_read_b128 v[86:89], v86 offset:3072
	ds_read_b128 v[146:149], v158
	ds_read_b128 v[150:153], v158 offset:1024
	ds_read_b128 v[154:157], v158 offset:2048
	ds_read_b128 v[158:161], v158 offset:3072
	v_lshl_add_u64 v[204:205], s[66:67], 0, v[172:173]
	s_add_i32 m0, s65, 0xc000
	ds_read_b128 v[174:177], v184
	ds_read_b128 v[178:181], v184 offset:1024
	ds_read_b128 v[186:189], v184 offset:2048
	ds_read_b128 v[190:193], v184 offset:3072
	ds_read_b128 v[200:203], v184 offset:4096
	ds_read_b128 v[206:209], v184 offset:5120
	ds_read_b128 v[210:213], v184 offset:6144
	ds_read_b128 v[214:217], v184 offset:7168
	global_load_lds_dwordx4 v[204:205], off
	v_lshl_add_u64 v[204:205], s[66:67], 0, v[170:171]
	s_add_i32 m0, s65, 0xe000
	s_nop 0
	global_load_lds_dwordx4 v[204:205], off
	s_waitcnt vmcnt(8)
	s_waitcnt lgkmcnt(0)
	s_barrier
	s_waitcnt lgkmcnt(0)
	v_mfma_f32_16x16x32_bf16 v[142:145], v[66:69], v[174:177], 0
	v_mfma_f32_16x16x32_bf16 v[138:141], v[82:85], v[174:177], 0
	v_mfma_f32_16x16x32_bf16 v[126:129], v[66:69], v[186:189], 0
	v_mfma_f32_16x16x32_bf16 v[122:125], v[82:85], v[186:189], 0
	v_mfma_f32_16x16x32_bf16 v[110:113], v[66:69], v[200:203], 0
	v_mfma_f32_16x16x32_bf16 v[106:109], v[82:85], v[200:203], 0
	v_mfma_f32_16x16x32_bf16 v[94:97], v[66:69], v[210:213], 0
	v_mfma_f32_16x16x32_bf16 v[90:93], v[82:85], v[210:213], 0
	v_mfma_f32_16x16x32_bf16 v[142:145], v[70:73], v[178:181], v[142:145]
	v_mfma_f32_16x16x32_bf16 v[138:141], v[86:89], v[178:181], v[138:141]
	v_mfma_f32_16x16x32_bf16 v[126:129], v[70:73], v[190:193], v[126:129]
	v_mfma_f32_16x16x32_bf16 v[122:125], v[86:89], v[190:193], v[122:125]
	v_mfma_f32_16x16x32_bf16 v[110:113], v[70:73], v[206:209], v[110:113]
	v_mfma_f32_16x16x32_bf16 v[106:109], v[86:89], v[206:209], v[106:109]
	v_mfma_f32_16x16x32_bf16 v[94:97], v[70:73], v[214:217], v[94:97]
	v_mfma_f32_16x16x32_bf16 v[90:93], v[86:89], v[214:217], v[90:93]
	v_mfma_f32_16x16x32_bf16 v[134:137], v[146:149], v[174:177], 0
	v_mfma_f32_16x16x32_bf16 v[130:133], v[154:157], v[174:177], 0
	v_mfma_f32_16x16x32_bf16 v[118:121], v[146:149], v[186:189], 0
	v_mfma_f32_16x16x32_bf16 v[114:117], v[154:157], v[186:189], 0
	v_mfma_f32_16x16x32_bf16 v[102:105], v[146:149], v[200:203], 0
	v_mfma_f32_16x16x32_bf16 v[98:101], v[154:157], v[200:203], 0
	v_mfma_f32_16x16x32_bf16 v[78:81], v[146:149], v[210:213], 0
	v_mfma_f32_16x16x32_bf16 v[74:77], v[154:157], v[210:213], 0
	v_mfma_f32_16x16x32_bf16 v[134:137], v[150:153], v[178:181], v[134:137]
	v_mfma_f32_16x16x32_bf16 v[130:133], v[158:161], v[178:181], v[130:133]
	v_mfma_f32_16x16x32_bf16 v[118:121], v[150:153], v[190:193], v[118:121]
	v_mfma_f32_16x16x32_bf16 v[114:117], v[158:161], v[190:193], v[114:117]
	v_mfma_f32_16x16x32_bf16 v[102:105], v[150:153], v[206:209], v[102:105]
	v_mfma_f32_16x16x32_bf16 v[98:101], v[158:161], v[206:209], v[98:101]
	v_mfma_f32_16x16x32_bf16 v[78:81], v[150:153], v[214:217], v[78:81]
	v_mfma_f32_16x16x32_bf16 v[74:77], v[158:161], v[214:217], v[74:77]
	s_barrier
	s_add_i32 s18, vcc_hi, s72
	v_lshl_add_u64 v[204:205], s[68:69], 0, v[164:165]
	s_mov_b32 m0, s18
	ds_read_b128 v[174:177], v184 offset:16384
	ds_read_b128 v[178:181], v184 offset:17408
	ds_read_b128 v[186:189], v184 offset:18432
	ds_read_b128 v[190:193], v184 offset:19456
	ds_read_b128 v[200:203], v184 offset:20480
	ds_read_b128 v[206:209], v184 offset:21504
	ds_read_b128 v[210:213], v184 offset:22528
	ds_read_b128 v[214:217], v184 offset:23552
	global_load_lds_dwordx4 v[204:205], off
	s_add_i32 m0, s18, 0x2000
	s_add_u32 s18, s68, 0x20000
	v_lshl_add_u64 v[218:219], s[68:69], 0, v[168:169]
	s_addc_u32 s19, s69, 0
	s_add_i32 s81, s81, s72
	global_load_lds_dwordx4 v[218:219], off
	v_lshl_add_u64 v[220:221], s[18:19], 0, v[164:165]
	s_mov_b32 m0, s81
	v_lshl_add_u64 v[222:223], s[70:71], 0, v[166:167]
	global_load_lds_dwordx4 v[220:221], off
	v_lshl_add_u64 v[220:221], s[18:19], 0, v[168:169]
	s_add_i32 m0, s81, 0x2000
	s_nop 0
	global_load_lds_dwordx4 v[220:221], off
	v_lshl_add_u64 v[220:221], s[70:71], 0, v[162:163]
	s_mov_b32 m0, s65
	s_nop 0
	global_load_lds_dwordx4 v[220:221], off
	s_mov_b32 m0, s73
	s_nop 0
	global_load_lds_dwordx4 v[222:223], off
	s_waitcnt vmcnt(8)
	s_waitcnt lgkmcnt(0)
	s_barrier
	s_waitcnt lgkmcnt(0)
	v_mfma_f32_16x16x32_bf16 v[62:65], v[66:69], v[174:177], 0
	v_mfma_f32_16x16x32_bf16 v[58:61], v[82:85], v[174:177], 0
	v_mfma_f32_16x16x32_bf16 v[46:49], v[66:69], v[186:189], 0
	v_mfma_f32_16x16x32_bf16 v[42:45], v[82:85], v[186:189], 0
	v_mfma_f32_16x16x32_bf16 v[30:33], v[66:69], v[200:203], 0
	v_mfma_f32_16x16x32_bf16 v[26:29], v[82:85], v[200:203], 0
	v_mfma_f32_16x16x32_bf16 v[14:17], v[66:69], v[210:213], 0
	v_mfma_f32_16x16x32_bf16 v[10:13], v[82:85], v[210:213], 0
	v_mfma_f32_16x16x32_bf16 v[62:65], v[70:73], v[178:181], v[62:65]
	v_mfma_f32_16x16x32_bf16 v[58:61], v[86:89], v[178:181], v[58:61]
	v_mfma_f32_16x16x32_bf16 v[46:49], v[70:73], v[190:193], v[46:49]
	v_mfma_f32_16x16x32_bf16 v[42:45], v[86:89], v[190:193], v[42:45]
	v_mfma_f32_16x16x32_bf16 v[30:33], v[70:73], v[206:209], v[30:33]
	v_mfma_f32_16x16x32_bf16 v[26:29], v[86:89], v[206:209], v[26:29]
	v_mfma_f32_16x16x32_bf16 v[14:17], v[70:73], v[214:217], v[14:17]
	v_mfma_f32_16x16x32_bf16 v[10:13], v[86:89], v[214:217], v[10:13]
	v_mfma_f32_16x16x32_bf16 v[54:57], v[146:149], v[174:177], 0
	v_mfma_f32_16x16x32_bf16 v[50:53], v[154:157], v[174:177], 0
	v_mfma_f32_16x16x32_bf16 v[38:41], v[146:149], v[186:189], 0
	v_mfma_f32_16x16x32_bf16 v[34:37], v[154:157], v[186:189], 0
	v_mfma_f32_16x16x32_bf16 v[22:25], v[146:149], v[200:203], 0
	v_mfma_f32_16x16x32_bf16 v[18:21], v[154:157], v[200:203], 0
	v_mfma_f32_16x16x32_bf16 v[6:9], v[146:149], v[210:213], 0
	v_mfma_f32_16x16x32_bf16 v[2:5], v[154:157], v[210:213], 0
	v_mfma_f32_16x16x32_bf16 v[54:57], v[150:153], v[178:181], v[54:57]
	v_mfma_f32_16x16x32_bf16 v[50:53], v[158:161], v[178:181], v[50:53]
	v_mfma_f32_16x16x32_bf16 v[38:41], v[150:153], v[190:193], v[38:41]
	v_mfma_f32_16x16x32_bf16 v[34:37], v[158:161], v[190:193], v[34:37]
	v_mfma_f32_16x16x32_bf16 v[22:25], v[150:153], v[206:209], v[22:25]
	v_mfma_f32_16x16x32_bf16 v[18:21], v[158:161], v[206:209], v[18:21]
	v_mfma_f32_16x16x32_bf16 v[6:9], v[150:153], v[214:217], v[6:9]
	v_mfma_f32_16x16x32_bf16 v[2:5], v[158:161], v[214:217], v[2:5]
	s_barrier
	s_branch .Lp3_post2

; #define PG8_STAGE(bufoff, gbase, voff) do { _Pragma("unroll") for (int _i = 0; _i < 2; ++_i) \
;         __builtin_amdgcn_global_load_lds((const unsigned*)((const char*)(gbase) + (voff)[_i]), (LAS unsigned*)(lds + (bufoff) + ldsw + _i * 8192), 16, 0, 0); } while (0)
; #define PG8_LDA(dst, b, h) do { _Pragma("unroll") for (int m = 0; m < 4; ++m) _Pragma("unroll") for (int k = 0; k < 2; ++k) dst[m][k] = *(const LAS bf16x8*)(lds + PG8_SA(b, h) + aoff + m * 2048 + k * 1024); } while (0)
; #define PG8_LDB(dst, b, h) do { _Pragma("unroll") for (int n = 0; n < 2; ++n) _Pragma("unroll") for (int k = 0; k < 2; ++k) dst[n][k] = *(const LAS bf16x8*)(lds + PG8_SB(b, h) + boff + n * 2048 + k * 1024); } while (0)
; #define PG8_MMA(ai, bj, At, Bt) do { __builtin_amdgcn_s_setprio(1); _Pragma("unroll") for (int m = 0; m < 4; ++m) _Pragma("unroll") for (int n = 0; n < 2; ++n) _Pragma("unroll") for (int k = 0; k < 2; ++k) \
;         acc[ai][bj][m][n] = __builtin_amdgcn_mfma_f32_16x16x32_bf16(Bt[n][k], At[m][k], acc[ai][bj][m][n], 0, 0, 0); __builtin_amdgcn_s_setprio(0); } while (0)
; #define PG8_WAIT_V(n) asm volatile("s_waitcnt vmcnt(" #n ")" ::: "memory")
; #define PG8_WAIT_L(n) asm volatile("s_waitcnt lgkmcnt(" #n ")" ::: "memory")
; #define PG8_BAR __builtin_amdgcn_s_barrier()
; #define PG8_SCHED __builtin_amdgcn_sched_barrier(0)
; template <class Epi>
; DI void gemm_phase(LAS unsigned char* lds, const Gemm g, const StaticOrder& S, const Epi& E) {
;     ...
;             PG8_LDB(B0, 1, 0); PG8_LDB(B1, 1, 1); PG8_SCHED; PG8_LDA(At, 1, 0); PG8_STAGE(PG8_SA(0, 1), a2 + hstep, voffA);
;             PG8_WAIT_V(8); PG8_WAIT_L(0); PG8_BAR; PG8_MMA(0, 0, At, B0); PG8_MMA(0, 1, At, B1); PG8_BAR; PG8_SCHED;
.Lp3_post2:
	s_add_i32 s81, 0, 0x18000
	s_add_i32 vcc_hi, 0, 0x1c000
	v_add_u32_e32 v86, s81, v182
	v_add_u32_e32 v158, vcc_hi, v182
	ds_read_b128 v[66:69], v86
	ds_read_b128 v[70:73], v86 offset:1024
	ds_read_b128 v[82:85], v86 offset:2048
	ds_read_b128 v[86:89], v86 offset:3072
	ds_read_b128 v[146:149], v158
	ds_read_b128 v[150:153], v158 offset:1024
	ds_read_b128 v[154:157], v158 offset:2048
	ds_read_b128 v[158:161], v158 offset:3072
	s_add_u32 s18, s70, 0x20000
	s_addc_u32 s19, s71, 0
	s_mov_b32 m0, s91
	v_lshl_add_u64 v[224:225], s[18:19], 0, v[162:163]
	ds_read_b128 v[174:177], v184 offset:32768
	ds_read_b128 v[178:181], v184 offset:33792
	ds_read_b128 v[186:189], v184 offset:34816
	ds_read_b128 v[190:193], v184 offset:35840
	ds_read_b128 v[200:203], v184 offset:36864
	ds_read_b128 v[206:209], v184 offset:37888
	ds_read_b128 v[210:213], v184 offset:38912
	ds_read_b128 v[214:217], v184 offset:39936
	global_load_lds_dwordx4 v[224:225], off
	v_lshl_add_u64 v[224:225], s[18:19], 0, v[166:167]
	s_mov_b32 m0, s93
	s_nop 0
	global_load_lds_dwordx4 v[224:225], off
	s_waitcnt vmcnt(8)
	s_waitcnt lgkmcnt(0)
	s_barrier
	s_waitcnt lgkmcnt(0)
	v_mfma_f32_16x16x32_bf16 v[142:145], v[66:69], v[174:177], v[142:145]
	v_mfma_f32_16x16x32_bf16 v[138:141], v[82:85], v[174:177], v[138:141]
	v_mfma_f32_16x16x32_bf16 v[126:129], v[66:69], v[186:189], v[126:129]
	v_mfma_f32_16x16x32_bf16 v[122:125], v[82:85], v[186:189], v[122:125]
	v_mfma_f32_16x16x32_bf16 v[110:113], v[66:69], v[200:203], v[110:113]
	v_mfma_f32_16x16x32_bf16 v[106:109], v[82:85], v[200:203], v[106:109]
	v_mfma_f32_16x16x32_bf16 v[94:97], v[66:69], v[210:213], v[94:97]
	v_mfma_f32_16x16x32_bf16 v[90:93], v[82:85], v[210:213], v[90:93]
	v_mfma_f32_16x16x32_bf16 v[142:145], v[70:73], v[178:181], v[142:145]
	v_mfma_f32_16x16x32_bf16 v[138:141], v[86:89], v[178:181], v[138:141]
	v_mfma_f32_16x16x32_bf16 v[126:129], v[70:73], v[190:193], v[126:129]
	v_mfma_f32_16x16x32_bf16 v[122:125], v[86:89], v[190:193], v[122:125]
	v_mfma_f32_16x16x32_bf16 v[110:113], v[70:73], v[206:209], v[110:113]
	v_mfma_f32_16x16x32_bf16 v[106:109], v[86:89], v[206:209], v[106:109]
	v_mfma_f32_16x16x32_bf16 v[94:97], v[70:73], v[214:217], v[94:97]
	v_mfma_f32_16x16x32_bf16 v[90:93], v[86:89], v[214:217], v[90:93]
	v_mfma_f32_16x16x32_bf16 v[134:137], v[146:149], v[174:177], v[134:137]
	v_mfma_f32_16x16x32_bf16 v[130:133], v[154:157], v[174:177], v[130:133]
	v_mfma_f32_16x16x32_bf16 v[118:121], v[146:149], v[186:189], v[118:121]
	v_mfma_f32_16x16x32_bf16 v[114:117], v[154:157], v[186:189], v[114:117]
	v_mfma_f32_16x16x32_bf16 v[102:105], v[146:149], v[200:203], v[102:105]
	v_mfma_f32_16x16x32_bf16 v[98:101], v[154:157], v[200:203], v[98:101]
	v_mfma_f32_16x16x32_bf16 v[78:81], v[146:149], v[210:213], v[78:81]
	v_mfma_f32_16x16x32_bf16 v[74:77], v[154:157], v[210:213], v[74:77]
	v_mfma_f32_16x16x32_bf16 v[134:137], v[150:153], v[178:181], v[134:137]
	v_mfma_f32_16x16x32_bf16 v[130:133], v[158:161], v[178:181], v[130:133]
	v_mfma_f32_16x16x32_bf16 v[118:121], v[150:153], v[190:193], v[118:121]
	v_mfma_f32_16x16x32_bf16 v[114:117], v[158:161], v[190:193], v[114:117]
	v_mfma_f32_16x16x32_bf16 v[102:105], v[150:153], v[206:209], v[102:105]
	v_mfma_f32_16x16x32_bf16 v[98:101], v[158:161], v[206:209], v[98:101]
	v_mfma_f32_16x16x32_bf16 v[78:81], v[150:153], v[214:217], v[78:81]
	v_mfma_f32_16x16x32_bf16 v[74:77], v[158:161], v[214:217], v[74:77]
	s_barrier
; #define PG8_STAGE(bufoff, gbase, voff) do { _Pragma("unroll") for (int _i = 0; _i < 2; ++_i) \
;         __builtin_amdgcn_global_load_lds((const unsigned*)((const char*)(gbase) + (voff)[_i]), (LAS unsigned*)(lds + (bufoff) + ldsw + _i * 8192), 16, 0, 0); } while (0)
; #define PG8_LDA(dst, b, h) do { _Pragma("unroll") for (int m = 0; m < 4; ++m) _Pragma("unroll") for (int k = 0; k < 2; ++k) dst[m][k] = *(const LAS bf16x8*)(lds + PG8_SA(b, h) + aoff + m * 2048 + k * 1024); } while (0)
; #define PG8_MMA(ai, bj, At, Bt) do { __builtin_amdgcn_s_setprio(1); _Pragma("unroll") for (int m = 0; m < 4; ++m) _Pragma("unroll") for (int n = 0; n < 2; ++n) _Pragma("unroll") for (int k = 0; k < 2; ++k) \
;         acc[ai][bj][m][n] = __builtin_amdgcn_mfma_f32_16x16x32_bf16(Bt[n][k], At[m][k], acc[ai][bj][m][n], 0, 0, 0); __builtin_amdgcn_s_setprio(0); } while (0)
; #define PG8_WAIT_V(n) asm volatile("s_waitcnt vmcnt(" #n ")" ::: "memory")
; #define PG8_WAIT_L(n) asm volatile("s_waitcnt lgkmcnt(" #n ")" ::: "memory")
; #define PG8_BAR __builtin_amdgcn_s_barrier()
; #define PG8_SCHED __builtin_amdgcn_sched_barrier(0)
; template <class Epi>
; DI void gemm_phase(LAS unsigned char* lds, const Gemm g, const StaticOrder& S, const Epi& E) {
;     ...
;             PG8_LDA(At, 1, 1); PG8_STAGE(PG8_SB(1, 0), b3, voffB); PG8_STAGE(PG8_SB(1, 1), b3 + hstep, voffB); PG8_STAGE(PG8_SA(1, 0), a3, voffA);
;             PG8_WAIT_V(8); PG8_WAIT_L(0); PG8_BAR; PG8_MMA(1, 0, At, B0); PG8_MMA(1, 1, At, B1); PG8_BAR; PG8_SCHED;
;         }
;         if (wr == 0) PG8_BAR;
	s_add_i32 s18, s81, s72
	v_lshl_add_u64 v[204:205], v[204:205], 0, s[20:21]
	s_mov_b32 m0, s18
	ds_read_b128 v[174:177], v184 offset:49152
	ds_read_b128 v[178:181], v184 offset:50176
	ds_read_b128 v[186:189], v184 offset:51200
	ds_read_b128 v[190:193], v184 offset:52224
	ds_read_b128 v[200:203], v184 offset:53248
	ds_read_b128 v[206:209], v184 offset:54272
	ds_read_b128 v[210:213], v184 offset:55296
	ds_read_b128 v[214:217], v184 offset:56320
	global_load_lds_dwordx4 v[204:205], off
	s_add_i32 m0, s18, 0x2000
	s_add_u32 s18, s68, 0x20080
	v_lshl_add_u64 v[204:205], v[218:219], 0, s[20:21]
	s_addc_u32 s19, s69, 0
	s_add_i32 s68, vcc_hi, s72
	global_load_lds_dwordx4 v[204:205], off
	v_lshl_add_u64 v[204:205], s[18:19], 0, v[164:165]
	s_mov_b32 m0, s68
	s_nop 0
	global_load_lds_dwordx4 v[204:205], off
	v_lshl_add_u64 v[204:205], s[18:19], 0, v[168:169]
	s_add_i32 m0, s68, 0x2000
	s_nop 0
	global_load_lds_dwordx4 v[204:205], off
	v_lshl_add_u64 v[204:205], v[220:221], 0, s[20:21]
	s_mov_b32 m0, s17
	s_nop 0
	global_load_lds_dwordx4 v[204:205], off
	v_lshl_add_u64 v[204:205], v[222:223], 0, s[20:21]
	s_mov_b32 m0, s42
	s_nop 0
	global_load_lds_dwordx4 v[204:205], off
	s_waitcnt vmcnt(8)
	s_waitcnt lgkmcnt(0)
	s_barrier
	s_waitcnt lgkmcnt(0)
	v_mfma_f32_16x16x32_bf16 v[62:65], v[66:69], v[174:177], v[62:65]
	v_mfma_f32_16x16x32_bf16 v[58:61], v[82:85], v[174:177], v[58:61]
	v_mfma_f32_16x16x32_bf16 v[46:49], v[66:69], v[186:189], v[46:49]
	v_mfma_f32_16x16x32_bf16 v[42:45], v[82:85], v[186:189], v[42:45]
	v_mfma_f32_16x16x32_bf16 v[30:33], v[66:69], v[200:203], v[30:33]
	v_mfma_f32_16x16x32_bf16 v[26:29], v[82:85], v[200:203], v[26:29]
	v_mfma_f32_16x16x32_bf16 v[14:17], v[66:69], v[210:213], v[14:17]
	v_mfma_f32_16x16x32_bf16 v[10:13], v[82:85], v[210:213], v[10:13]
	v_mfma_f32_16x16x32_bf16 v[62:65], v[70:73], v[178:181], v[62:65]
	v_mfma_f32_16x16x32_bf16 v[58:61], v[86:89], v[178:181], v[58:61]
	v_mfma_f32_16x16x32_bf16 v[46:49], v[70:73], v[190:193], v[46:49]
	v_mfma_f32_16x16x32_bf16 v[42:45], v[86:89], v[190:193], v[42:45]
	v_mfma_f32_16x16x32_bf16 v[30:33], v[70:73], v[206:209], v[30:33]
	v_mfma_f32_16x16x32_bf16 v[26:29], v[86:89], v[206:209], v[26:29]
	v_mfma_f32_16x16x32_bf16 v[14:17], v[70:73], v[214:217], v[14:17]
	v_mfma_f32_16x16x32_bf16 v[10:13], v[86:89], v[214:217], v[10:13]
	v_mfma_f32_16x16x32_bf16 v[54:57], v[146:149], v[174:177], v[54:57]
	v_mfma_f32_16x16x32_bf16 v[50:53], v[154:157], v[174:177], v[50:53]
	v_mfma_f32_16x16x32_bf16 v[38:41], v[146:149], v[186:189], v[38:41]
	v_mfma_f32_16x16x32_bf16 v[34:37], v[154:157], v[186:189], v[34:37]
	v_mfma_f32_16x16x32_bf16 v[22:25], v[146:149], v[200:203], v[22:25]
	v_mfma_f32_16x16x32_bf16 v[18:21], v[154:157], v[200:203], v[18:21]
	v_mfma_f32_16x16x32_bf16 v[6:9], v[146:149], v[210:213], v[6:9]
	v_mfma_f32_16x16x32_bf16 v[2:5], v[154:157], v[210:213], v[2:5]
	v_mfma_f32_16x16x32_bf16 v[54:57], v[150:153], v[178:181], v[54:57]
	v_mfma_f32_16x16x32_bf16 v[50:53], v[158:161], v[178:181], v[50:53]
	v_mfma_f32_16x16x32_bf16 v[38:41], v[150:153], v[190:193], v[38:41]
	v_mfma_f32_16x16x32_bf16 v[34:37], v[158:161], v[190:193], v[34:37]
	v_mfma_f32_16x16x32_bf16 v[22:25], v[150:153], v[206:209], v[22:25]
	v_mfma_f32_16x16x32_bf16 v[18:21], v[158:161], v[206:209], v[18:21]
	v_mfma_f32_16x16x32_bf16 v[6:9], v[150:153], v[214:217], v[6:9]
	v_mfma_f32_16x16x32_bf16 v[2:5], v[158:161], v[214:217], v[2:5]
	s_barrier
	s_add_i32 vcc_lo, vcc_lo, 2
	s_add_u32 s94, s94, 0x100
	s_addc_u32 s95, s95, 0
	s_add_u32 s66, s66, 0x100
	s_addc_u32 s67, s67, 0
	s_cmp_gt_u32 vcc_lo, 5
	s_cbranch_scc0 .LBB0_539
	s_setprio 0
	s_and_b64 vcc, exec, s[54:55]
	s_cbranch_vccz .LBB0_542
	s_barrier

; template <class Epi>
; DI void gemm_phase(LAS unsigned char* lds, const Gemm g, const StaticOrder& S, const Epi& E) {
;     ...
;         const bool has_next = S.next(ui + 1, nxt);
;         const char* nA = has_next ? (const char*)g.A + (size_t)nxt.pm * tstep : cA; const char* nB = has_next ? (const char*)g.Bt + (size_t)nxt.pn * tstep : cB;
;         for (int t = 0; t < nt; t += 2) {
;             const bool last = (t == nt - 2);
;             const char* a1 = cA + (size_t)(t + 1) * kstep;
;             const char* a2 = last ? nA : cA + (size_t)(t + 2) * kstep; const char* b2 = last ? nB : cB + (size_t)(t + 2) * kstep;
;             const char* a3 = a2 + kstep; const char* b3 = b2 + kstep;
.LBB0_616:
	s_ashr_i32 s57, s56, 31
	s_lshl_b64 s[18:19], s[56:57], 19
	s_add_u32 s58, s25, s18
	s_addc_u32 s59, s30, s19
	s_and_b64 s[18:19], s[6:7], exec
	s_cselect_b32 s12, s59, s67
	s_cselect_b32 s23, s58, s66
	s_ashr_i32 s55, s54, 31
	s_lshl_b64 s[18:19], s[54:55], 19
	s_add_u32 s60, s31, s18
	s_addc_u32 s61, s36, s19
	s_and_b64 s[18:19], s[6:7], exec
	s_cselect_b32 s55, s61, s69
	s_cselect_b32 s57, s60, s68
	s_add_u32 s63, s68, 0x100
	s_addc_u32 s65, s69, 0
	s_mov_b32 vcc_lo, -2
	s_waitcnt lgkmcnt(0)
	v_readfirstlane_b32 s101, v242
	s_nop 3
	s_lshr_b32 s101, s101, 8
	s_cmp_eq_u32 s101, 0
	s_cbranch_scc0 .Lsp_2
	s_setprio 1
; #define PG8_STAGE(bufoff, gbase, voff) do { _Pragma("unroll") for (int _i = 0; _i < 2; ++_i) \
;         __builtin_amdgcn_global_load_lds((const unsigned*)((const char*)(gbase) + (voff)[_i]), (LAS unsigned*)(lds + (bufoff) + ldsw + _i * 8192), 16, 0, 0); } while (0)
; #define PG8_LDA(dst, b, h) do { _Pragma("unroll") for (int m = 0; m < 4; ++m) _Pragma("unroll") for (int k = 0; k < 2; ++k) dst[m][k] = *(const LAS bf16x8*)(lds + PG8_SA(b, h) + aoff + m * 2048 + k * 1024); } while (0)
; #define PG8_LDB(dst, b, h) do { _Pragma("unroll") for (int n = 0; n < 2; ++n) _Pragma("unroll") for (int k = 0; k < 2; ++k) dst[n][k] = *(const LAS bf16x8*)(lds + PG8_SB(b, h) + boff + n * 2048 + k * 1024); } while (0)
; #define PG8_MMA(ai, bj, At, Bt) do { __builtin_amdgcn_s_setprio(1); _Pragma("unroll") for (int m = 0; m < 4; ++m) _Pragma("unroll") for (int n = 0; n < 2; ++n) _Pragma("unroll") for (int k = 0; k < 2; ++k) \
;         acc[ai][bj][m][n] = __builtin_amdgcn_mfma_f32_16x16x32_bf16(Bt[n][k], At[m][k], acc[ai][bj][m][n], 0, 0, 0); __builtin_amdgcn_s_setprio(0); } while (0)
; #define PG8_WAIT_V(n) asm volatile("s_waitcnt vmcnt(" #n ")" ::: "memory")
; #define PG8_WAIT_L(n) asm volatile("s_waitcnt lgkmcnt(" #n ")" ::: "memory")
; #define PG8_BAR __builtin_amdgcn_s_barrier()
; #define PG8_SCHED __builtin_amdgcn_sched_barrier(0)
; template <class Epi>
; DI void gemm_phase(LAS unsigned char* lds, const Gemm g, const StaticOrder& S, const Epi& E) {
;     ...
;             PG8_LDB(B0, 0, 0); PG8_LDB(B1, 0, 1); PG8_SCHED; PG8_LDA(At, 0, 0); PG8_STAGE(PG8_SA(1, 1), a1 + hstep, voffA);
;             PG8_WAIT_V(8); PG8_WAIT_L(0); PG8_BAR; PG8_MMA(0, 0, At, B0); PG8_MMA(0, 1, At, B1); PG8_BAR; PG8_SCHED;
;             PG8_LDA(At, 0, 1); PG8_STAGE(PG8_SB(0, 0), b2, voffB); PG8_STAGE(PG8_SB(0, 1), b2 + hstep, voffB); PG8_STAGE(PG8_SA(0, 0), a2, voffA);
;             PG8_WAIT_V(8); PG8_WAIT_L(0); PG8_BAR; PG8_MMA(1, 0, At, B0); PG8_MMA(1, 1, At, B1); PG8_BAR; PG8_SCHED;
.Lsp_2:
	s_add_u32 s68, s66, 0x100
	s_addc_u32 s69, s67, 0
	s_add_i32 s18, 0, 0x10000
	s_cmp_eq_u32 vcc_lo, 12
	s_cselect_b32 s73, s12, s69
	s_cselect_b32 s72, s23, s68
	s_cselect_b32 s71, s55, s65
	s_cselect_b32 s70, s57, s63
	s_add_i32 s81, 0, 0x14000
	v_add_u32_e32 v126, s18, v195
	v_add_u32_e32 v154, s81, v195
	ds_read_b128 v[114:117], v126
	ds_read_b128 v[118:121], v126 offset:1024
	ds_read_b128 v[122:125], v126 offset:2048
	ds_read_b128 v[126:129], v126 offset:3072
	ds_read_b128 v[134:137], v154
	ds_read_b128 v[138:141], v154 offset:1024
	ds_read_b128 v[146:149], v154 offset:2048
	ds_read_b128 v[154:157], v154 offset:3072
	v_lshl_add_u64 v[204:205], s[66:67], 0, v[184:185]
	s_add_i32 m0, s93, 0xc000
	ds_read_b128 v[162:165], v217
	ds_read_b128 v[166:169], v217 offset:1024
	ds_read_b128 v[170:173], v217 offset:2048
	ds_read_b128 v[174:177], v217 offset:3072
	ds_read_b128 v[186:189], v217 offset:4096
	ds_read_b128 v[190:193], v217 offset:5120
	ds_read_b128 v[200:203], v217 offset:6144
	ds_read_b128 v[206:209], v217 offset:7168
	global_load_lds_dwordx4 v[204:205], off
	v_lshl_add_u64 v[204:205], s[66:67], 0, v[182:183]
	s_add_i32 m0, s93, 0xe000
	s_nop 0
	global_load_lds_dwordx4 v[204:205], off
	s_waitcnt vmcnt(8)
	s_waitcnt lgkmcnt(0)
	s_barrier
	s_waitcnt lgkmcnt(0)
	v_mfma_f32_16x16x32_bf16 v[158:161], v[114:117], v[162:165], 0
	v_mfma_f32_16x16x32_bf16 v[150:153], v[122:125], v[162:165], 0
	v_mfma_f32_16x16x32_bf16 v[110:113], v[114:117], v[170:173], 0
	v_mfma_f32_16x16x32_bf16 v[106:109], v[122:125], v[170:173], 0
	v_mfma_f32_16x16x32_bf16 v[94:97], v[114:117], v[186:189], 0
	v_mfma_f32_16x16x32_bf16 v[90:93], v[122:125], v[186:189], 0
	v_mfma_f32_16x16x32_bf16 v[78:81], v[114:117], v[200:203], 0
	v_mfma_f32_16x16x32_bf16 v[74:77], v[122:125], v[200:203], 0
	v_mfma_f32_16x16x32_bf16 v[158:161], v[118:121], v[166:169], v[158:161]
	v_mfma_f32_16x16x32_bf16 v[150:153], v[126:129], v[166:169], v[150:153]
	v_mfma_f32_16x16x32_bf16 v[110:113], v[118:121], v[174:177], v[110:113]
	v_mfma_f32_16x16x32_bf16 v[106:109], v[126:129], v[174:177], v[106:109]
	v_mfma_f32_16x16x32_bf16 v[94:97], v[118:121], v[190:193], v[94:97]
	v_mfma_f32_16x16x32_bf16 v[90:93], v[126:129], v[190:193], v[90:93]
	v_mfma_f32_16x16x32_bf16 v[78:81], v[118:121], v[206:209], v[78:81]
	v_mfma_f32_16x16x32_bf16 v[74:77], v[126:129], v[206:209], v[74:77]
	v_mfma_f32_16x16x32_bf16 v[142:145], v[134:137], v[162:165], 0
	v_mfma_f32_16x16x32_bf16 v[130:133], v[146:149], v[162:165], 0
	v_mfma_f32_16x16x32_bf16 v[102:105], v[134:137], v[170:173], 0
	v_mfma_f32_16x16x32_bf16 v[98:101], v[146:149], v[170:173], 0
	v_mfma_f32_16x16x32_bf16 v[86:89], v[134:137], v[186:189], 0
	v_mfma_f32_16x16x32_bf16 v[82:85], v[146:149], v[186:189], 0
	v_mfma_f32_16x16x32_bf16 v[70:73], v[134:137], v[200:203], 0
	v_mfma_f32_16x16x32_bf16 v[66:69], v[146:149], v[200:203], 0
	v_mfma_f32_16x16x32_bf16 v[142:145], v[138:141], v[166:169], v[142:145]
	v_mfma_f32_16x16x32_bf16 v[130:133], v[154:157], v[166:169], v[130:133]
	v_mfma_f32_16x16x32_bf16 v[102:105], v[138:141], v[174:177], v[102:105]
	v_mfma_f32_16x16x32_bf16 v[98:101], v[154:157], v[174:177], v[98:101]
	v_mfma_f32_16x16x32_bf16 v[86:89], v[138:141], v[190:193], v[86:89]
	v_mfma_f32_16x16x32_bf16 v[82:85], v[154:157], v[190:193], v[82:85]
	v_mfma_f32_16x16x32_bf16 v[70:73], v[138:141], v[206:209], v[70:73]
	v_mfma_f32_16x16x32_bf16 v[66:69], v[154:157], v[206:209], v[66:69]
	s_barrier
	s_add_i32 s18, s18, s37
	v_lshl_add_u64 v[204:205], s[70:71], 0, v[178:179]
	s_mov_b32 m0, s18
	ds_read_b128 v[162:165], v217 offset:16384
	ds_read_b128 v[166:169], v217 offset:17408
	ds_read_b128 v[170:173], v217 offset:18432
	ds_read_b128 v[174:177], v217 offset:19456
	ds_read_b128 v[186:189], v217 offset:20480
	ds_read_b128 v[190:193], v217 offset:21504
	ds_read_b128 v[200:203], v217 offset:22528
	ds_read_b128 v[206:209], v217 offset:23552
	global_load_lds_dwordx4 v[204:205], off
	s_add_i32 m0, s18, 0x2000
	s_add_u32 s18, s70, 0x40000
	v_lshl_add_u64 v[210:211], s[70:71], 0, v[180:181]
	s_addc_u32 s19, s71, 0
	s_add_i32 s66, s81, s37
	global_load_lds_dwordx4 v[210:211], off
	v_lshl_add_u64 v[212:213], s[18:19], 0, v[178:179]
	s_mov_b32 m0, s66
	v_lshl_add_u64 v[214:215], s[72:73], 0, v[180:181]
	global_load_lds_dwordx4 v[212:213], off
	v_lshl_add_u64 v[212:213], s[18:19], 0, v[180:181]
	s_add_i32 m0, s66, 0x2000
	s_nop 0
	global_load_lds_dwordx4 v[212:213], off
	v_lshl_add_u64 v[212:213], s[72:73], 0, v[178:179]
	s_mov_b32 m0, s93
	s_nop 0
	global_load_lds_dwordx4 v[212:213], off
	s_mov_b32 m0, s94
	s_nop 0
	global_load_lds_dwordx4 v[214:215], off
	s_waitcnt vmcnt(8)
	s_waitcnt lgkmcnt(0)
	s_barrier
	s_waitcnt lgkmcnt(0)
	v_mfma_f32_16x16x32_bf16 v[62:65], v[114:117], v[162:165], 0
	v_mfma_f32_16x16x32_bf16 v[58:61], v[122:125], v[162:165], 0
	v_mfma_f32_16x16x32_bf16 v[46:49], v[114:117], v[170:173], 0
	v_mfma_f32_16x16x32_bf16 v[42:45], v[122:125], v[170:173], 0
	v_mfma_f32_16x16x32_bf16 v[30:33], v[114:117], v[186:189], 0
	v_mfma_f32_16x16x32_bf16 v[26:29], v[122:125], v[186:189], 0
	v_mfma_f32_16x16x32_bf16 v[14:17], v[114:117], v[200:203], 0
	v_mfma_f32_16x16x32_bf16 v[10:13], v[122:125], v[200:203], 0
	v_mfma_f32_16x16x32_bf16 v[62:65], v[118:121], v[166:169], v[62:65]
	v_mfma_f32_16x16x32_bf16 v[58:61], v[126:129], v[166:169], v[58:61]
	v_mfma_f32_16x16x32_bf16 v[46:49], v[118:121], v[174:177], v[46:49]
	v_mfma_f32_16x16x32_bf16 v[42:45], v[126:129], v[174:177], v[42:45]
	v_mfma_f32_16x16x32_bf16 v[30:33], v[118:121], v[190:193], v[30:33]
	v_mfma_f32_16x16x32_bf16 v[26:29], v[126:129], v[190:193], v[26:29]
	v_mfma_f32_16x16x32_bf16 v[14:17], v[118:121], v[206:209], v[14:17]
	v_mfma_f32_16x16x32_bf16 v[10:13], v[126:129], v[206:209], v[10:13]
	v_mfma_f32_16x16x32_bf16 v[54:57], v[134:137], v[162:165], 0
	v_mfma_f32_16x16x32_bf16 v[50:53], v[146:149], v[162:165], 0
	v_mfma_f32_16x16x32_bf16 v[38:41], v[134:137], v[170:173], 0
	v_mfma_f32_16x16x32_bf16 v[34:37], v[146:149], v[170:173], 0
	v_mfma_f32_16x16x32_bf16 v[22:25], v[134:137], v[186:189], 0
	v_mfma_f32_16x16x32_bf16 v[18:21], v[146:149], v[186:189], 0
	v_mfma_f32_16x16x32_bf16 v[6:9], v[134:137], v[200:203], 0
	v_mfma_f32_16x16x32_bf16 v[2:5], v[146:149], v[200:203], 0
	v_mfma_f32_16x16x32_bf16 v[54:57], v[138:141], v[166:169], v[54:57]
	v_mfma_f32_16x16x32_bf16 v[50:53], v[154:157], v[166:169], v[50:53]
	v_mfma_f32_16x16x32_bf16 v[38:41], v[138:141], v[174:177], v[38:41]
	v_mfma_f32_16x16x32_bf16 v[34:37], v[154:157], v[174:177], v[34:37]
	v_mfma_f32_16x16x32_bf16 v[22:25], v[138:141], v[190:193], v[22:25]
	v_mfma_f32_16x16x32_bf16 v[18:21], v[154:157], v[190:193], v[18:21]
	v_mfma_f32_16x16x32_bf16 v[6:9], v[138:141], v[206:209], v[6:9]
	v_mfma_f32_16x16x32_bf16 v[2:5], v[154:157], v[206:209], v[2:5]
	s_barrier
	s_branch .Lp3_out

; #define PG8_STAGE(bufoff, gbase, voff) do { _Pragma("unroll") for (int _i = 0; _i < 2; ++_i) \
;         __builtin_amdgcn_global_load_lds((const unsigned*)((const char*)(gbase) + (voff)[_i]), (LAS unsigned*)(lds + (bufoff) + ldsw + _i * 8192), 16, 0, 0); } while (0)
; #define PG8_LDA(dst, b, h) do { _Pragma("unroll") for (int m = 0; m < 4; ++m) _Pragma("unroll") for (int k = 0; k < 2; ++k) dst[m][k] = *(const LAS bf16x8*)(lds + PG8_SA(b, h) + aoff + m * 2048 + k * 1024); } while (0)
; #define PG8_LDB(dst, b, h) do { _Pragma("unroll") for (int n = 0; n < 2; ++n) _Pragma("unroll") for (int k = 0; k < 2; ++k) dst[n][k] = *(const LAS bf16x8*)(lds + PG8_SB(b, h) + boff + n * 2048 + k * 1024); } while (0)
; #define PG8_MMA(ai, bj, At, Bt) do { __builtin_amdgcn_s_setprio(1); _Pragma("unroll") for (int m = 0; m < 4; ++m) _Pragma("unroll") for (int n = 0; n < 2; ++n) _Pragma("unroll") for (int k = 0; k < 2; ++k) \
;         acc[ai][bj][m][n] = __builtin_amdgcn_mfma_f32_16x16x32_bf16(Bt[n][k], At[m][k], acc[ai][bj][m][n], 0, 0, 0); __builtin_amdgcn_s_setprio(0); } while (0)
; #define PG8_WAIT_V(n) asm volatile("s_waitcnt vmcnt(" #n ")" ::: "memory")
; #define PG8_WAIT_L(n) asm volatile("s_waitcnt lgkmcnt(" #n ")" ::: "memory")
; #define PG8_BAR __builtin_amdgcn_s_barrier()
; #define PG8_SCHED __builtin_amdgcn_sched_barrier(0)
; template <class Epi>
; DI void gemm_phase(LAS unsigned char* lds, const Gemm g, const StaticOrder& S, const Epi& E) {
;     ...
;             PG8_LDB(B0, 1, 0); PG8_LDB(B1, 1, 1); PG8_SCHED; PG8_LDA(At, 1, 0); PG8_STAGE(PG8_SA(0, 1), a2 + hstep, voffA);
;             PG8_WAIT_V(8); PG8_WAIT_L(0); PG8_BAR; PG8_MMA(0, 0, At, B0); PG8_MMA(0, 1, At, B1); PG8_BAR; PG8_SCHED;
.Lp3_out:
	s_add_i32 s66, 0, 0x18000
	s_add_i32 s67, 0, 0x1c000
	v_add_u32_e32 v126, s66, v195
	v_add_u32_e32 v154, s67, v195
	ds_read_b128 v[114:117], v126
	ds_read_b128 v[118:121], v126 offset:1024
	ds_read_b128 v[122:125], v126 offset:2048
	ds_read_b128 v[126:129], v126 offset:3072
	ds_read_b128 v[134:137], v154
	ds_read_b128 v[138:141], v154 offset:1024
	ds_read_b128 v[146:149], v154 offset:2048
	ds_read_b128 v[154:157], v154 offset:3072
	s_add_u32 s18, s72, 0x40000
	s_addc_u32 s19, s73, 0
	s_mov_b32 m0, s95
	v_lshl_add_u64 v[218:219], s[18:19], 0, v[178:179]
	ds_read_b128 v[162:165], v217 offset:32768
	ds_read_b128 v[166:169], v217 offset:33792
	ds_read_b128 v[170:173], v217 offset:34816
	ds_read_b128 v[174:177], v217 offset:35840
	ds_read_b128 v[186:189], v217 offset:36864
	ds_read_b128 v[190:193], v217 offset:37888
	ds_read_b128 v[200:203], v217 offset:38912
	ds_read_b128 v[206:209], v217 offset:39936
	global_load_lds_dwordx4 v[218:219], off
	v_lshl_add_u64 v[218:219], s[18:19], 0, v[180:181]
	s_mov_b32 m0, s91
	s_nop 0
	global_load_lds_dwordx4 v[218:219], off
	s_waitcnt vmcnt(8)
	s_waitcnt lgkmcnt(0)
	s_barrier
	s_waitcnt lgkmcnt(0)
	v_mfma_f32_16x16x32_bf16 v[158:161], v[114:117], v[162:165], v[158:161]
	v_mfma_f32_16x16x32_bf16 v[150:153], v[122:125], v[162:165], v[150:153]
	v_mfma_f32_16x16x32_bf16 v[110:113], v[114:117], v[170:173], v[110:113]
	v_mfma_f32_16x16x32_bf16 v[106:109], v[122:125], v[170:173], v[106:109]
	v_mfma_f32_16x16x32_bf16 v[94:97], v[114:117], v[186:189], v[94:97]
	v_mfma_f32_16x16x32_bf16 v[90:93], v[122:125], v[186:189], v[90:93]
	v_mfma_f32_16x16x32_bf16 v[78:81], v[114:117], v[200:203], v[78:81]
	v_mfma_f32_16x16x32_bf16 v[74:77], v[122:125], v[200:203], v[74:77]
	v_mfma_f32_16x16x32_bf16 v[158:161], v[118:121], v[166:169], v[158:161]
	v_mfma_f32_16x16x32_bf16 v[150:153], v[126:129], v[166:169], v[150:153]
	v_mfma_f32_16x16x32_bf16 v[110:113], v[118:121], v[174:177], v[110:113]
	v_mfma_f32_16x16x32_bf16 v[106:109], v[126:129], v[174:177], v[106:109]
	v_mfma_f32_16x16x32_bf16 v[94:97], v[118:121], v[190:193], v[94:97]
	v_mfma_f32_16x16x32_bf16 v[90:93], v[126:129], v[190:193], v[90:93]
	v_mfma_f32_16x16x32_bf16 v[78:81], v[118:121], v[206:209], v[78:81]
	v_mfma_f32_16x16x32_bf16 v[74:77], v[126:129], v[206:209], v[74:77]
	v_mfma_f32_16x16x32_bf16 v[142:145], v[134:137], v[162:165], v[142:145]
	v_mfma_f32_16x16x32_bf16 v[130:133], v[146:149], v[162:165], v[130:133]
	v_mfma_f32_16x16x32_bf16 v[102:105], v[134:137], v[170:173], v[102:105]
	v_mfma_f32_16x16x32_bf16 v[98:101], v[146:149], v[170:173], v[98:101]
	v_mfma_f32_16x16x32_bf16 v[86:89], v[134:137], v[186:189], v[86:89]
	v_mfma_f32_16x16x32_bf16 v[82:85], v[146:149], v[186:189], v[82:85]
	v_mfma_f32_16x16x32_bf16 v[70:73], v[134:137], v[200:203], v[70:73]
	v_mfma_f32_16x16x32_bf16 v[66:69], v[146:149], v[200:203], v[66:69]
	v_mfma_f32_16x16x32_bf16 v[142:145], v[138:141], v[166:169], v[142:145]
	v_mfma_f32_16x16x32_bf16 v[130:133], v[154:157], v[166:169], v[130:133]
	v_mfma_f32_16x16x32_bf16 v[102:105], v[138:141], v[174:177], v[102:105]
	v_mfma_f32_16x16x32_bf16 v[98:101], v[154:157], v[174:177], v[98:101]
	v_mfma_f32_16x16x32_bf16 v[86:89], v[138:141], v[190:193], v[86:89]
	v_mfma_f32_16x16x32_bf16 v[82:85], v[154:157], v[190:193], v[82:85]
	v_mfma_f32_16x16x32_bf16 v[70:73], v[138:141], v[206:209], v[70:73]
	v_mfma_f32_16x16x32_bf16 v[66:69], v[154:157], v[206:209], v[66:69]
	s_barrier
; #define PG8_STAGE(bufoff, gbase, voff) do { _Pragma("unroll") for (int _i = 0; _i < 2; ++_i) \
;         __builtin_amdgcn_global_load_lds((const unsigned*)((const char*)(gbase) + (voff)[_i]), (LAS unsigned*)(lds + (bufoff) + ldsw + _i * 8192), 16, 0, 0); } while (0)
; #define PG8_LDA(dst, b, h) do { _Pragma("unroll") for (int m = 0; m < 4; ++m) _Pragma("unroll") for (int k = 0; k < 2; ++k) dst[m][k] = *(const LAS bf16x8*)(lds + PG8_SA(b, h) + aoff + m * 2048 + k * 1024); } while (0)
; #define PG8_MMA(ai, bj, At, Bt) do { __builtin_amdgcn_s_setprio(1); _Pragma("unroll") for (int m = 0; m < 4; ++m) _Pragma("unroll") for (int n = 0; n < 2; ++n) _Pragma("unroll") for (int k = 0; k < 2; ++k) \
;         acc[ai][bj][m][n] = __builtin_amdgcn_mfma_f32_16x16x32_bf16(Bt[n][k], At[m][k], acc[ai][bj][m][n], 0, 0, 0); __builtin_amdgcn_s_setprio(0); } while (0)
; #define PG8_WAIT_V(n) asm volatile("s_waitcnt vmcnt(" #n ")" ::: "memory")
; #define PG8_WAIT_L(n) asm volatile("s_waitcnt lgkmcnt(" #n ")" ::: "memory")
; #define PG8_BAR __builtin_amdgcn_s_barrier()
; #define PG8_SCHED __builtin_amdgcn_sched_barrier(0)
; template <class Epi>
; DI void gemm_phase(LAS unsigned char* lds, const Gemm g, const StaticOrder& S, const Epi& E) {
;     ...
;             PG8_LDA(At, 1, 1); PG8_STAGE(PG8_SB(1, 0), b3, voffB); PG8_STAGE(PG8_SB(1, 1), b3 + hstep, voffB); PG8_STAGE(PG8_SA(1, 0), a3, voffA);
;             PG8_WAIT_V(8); PG8_WAIT_L(0); PG8_BAR; PG8_MMA(1, 0, At, B0); PG8_MMA(1, 1, At, B1); PG8_BAR; PG8_SCHED;
;         }
;         if (wr == 0) PG8_BAR;
;         E(acc, cur, wr, wc, fr, fq);
;         if (!has_next) break;
	s_add_i32 s18, s66, s37
	v_lshl_add_u64 v[204:205], v[204:205], 0, s[20:21]
	s_mov_b32 m0, s18
	ds_read_b128 v[162:165], v217 offset:49152
	ds_read_b128 v[166:169], v217 offset:50176
	ds_read_b128 v[170:173], v217 offset:51200
	ds_read_b128 v[174:177], v217 offset:52224
	ds_read_b128 v[186:189], v217 offset:53248
	ds_read_b128 v[190:193], v217 offset:54272
	ds_read_b128 v[200:203], v217 offset:55296
	ds_read_b128 v[206:209], v217 offset:56320
	global_load_lds_dwordx4 v[204:205], off
	s_add_i32 m0, s18, 0x2000
	s_add_u32 s18, s70, 0x40080
	v_lshl_add_u64 v[204:205], v[210:211], 0, s[20:21]
	s_addc_u32 s19, s71, 0
	s_add_i32 s66, s67, s37
	global_load_lds_dwordx4 v[204:205], off
	v_lshl_add_u64 v[204:205], s[18:19], 0, v[178:179]
	s_mov_b32 m0, s66
	s_nop 0
	global_load_lds_dwordx4 v[204:205], off
	v_lshl_add_u64 v[204:205], s[18:19], 0, v[180:181]
	s_add_i32 m0, s66, 0x2000
	s_nop 0
	global_load_lds_dwordx4 v[204:205], off
	v_lshl_add_u64 v[204:205], v[212:213], 0, s[20:21]
	s_mov_b32 m0, s17
	s_nop 0
	global_load_lds_dwordx4 v[204:205], off
	v_lshl_add_u64 v[204:205], v[214:215], 0, s[20:21]
	s_mov_b32 m0, s42
	s_nop 0
	global_load_lds_dwordx4 v[204:205], off
	s_waitcnt vmcnt(8)
	s_waitcnt lgkmcnt(0)
	s_barrier
	s_waitcnt lgkmcnt(0)
	v_mfma_f32_16x16x32_bf16 v[62:65], v[114:117], v[162:165], v[62:65]
	v_mfma_f32_16x16x32_bf16 v[58:61], v[122:125], v[162:165], v[58:61]
	v_mfma_f32_16x16x32_bf16 v[46:49], v[114:117], v[170:173], v[46:49]
	v_mfma_f32_16x16x32_bf16 v[42:45], v[122:125], v[170:173], v[42:45]
	v_mfma_f32_16x16x32_bf16 v[30:33], v[114:117], v[186:189], v[30:33]
	v_mfma_f32_16x16x32_bf16 v[26:29], v[122:125], v[186:189], v[26:29]
	v_mfma_f32_16x16x32_bf16 v[14:17], v[114:117], v[200:203], v[14:17]
	v_mfma_f32_16x16x32_bf16 v[10:13], v[122:125], v[200:203], v[10:13]
	v_mfma_f32_16x16x32_bf16 v[62:65], v[118:121], v[166:169], v[62:65]
	v_mfma_f32_16x16x32_bf16 v[58:61], v[126:129], v[166:169], v[58:61]
	v_mfma_f32_16x16x32_bf16 v[46:49], v[118:121], v[174:177], v[46:49]
	v_mfma_f32_16x16x32_bf16 v[42:45], v[126:129], v[174:177], v[42:45]
	v_mfma_f32_16x16x32_bf16 v[30:33], v[118:121], v[190:193], v[30:33]
	v_mfma_f32_16x16x32_bf16 v[26:29], v[126:129], v[190:193], v[26:29]
	v_mfma_f32_16x16x32_bf16 v[14:17], v[118:121], v[206:209], v[14:17]
	v_mfma_f32_16x16x32_bf16 v[10:13], v[126:129], v[206:209], v[10:13]
	v_mfma_f32_16x16x32_bf16 v[54:57], v[134:137], v[162:165], v[54:57]
	v_mfma_f32_16x16x32_bf16 v[50:53], v[146:149], v[162:165], v[50:53]
	v_mfma_f32_16x16x32_bf16 v[38:41], v[134:137], v[170:173], v[38:41]
	v_mfma_f32_16x16x32_bf16 v[34:37], v[146:149], v[170:173], v[34:37]
	v_mfma_f32_16x16x32_bf16 v[22:25], v[134:137], v[186:189], v[22:25]
	v_mfma_f32_16x16x32_bf16 v[18:21], v[146:149], v[186:189], v[18:21]
	v_mfma_f32_16x16x32_bf16 v[6:9], v[134:137], v[200:203], v[6:9]
	v_mfma_f32_16x16x32_bf16 v[2:5], v[146:149], v[200:203], v[2:5]
	v_mfma_f32_16x16x32_bf16 v[54:57], v[138:141], v[166:169], v[54:57]
	v_mfma_f32_16x16x32_bf16 v[50:53], v[154:157], v[166:169], v[50:53]
	v_mfma_f32_16x16x32_bf16 v[38:41], v[138:141], v[174:177], v[38:41]
	v_mfma_f32_16x16x32_bf16 v[34:37], v[154:157], v[174:177], v[34:37]
	v_mfma_f32_16x16x32_bf16 v[22:25], v[138:141], v[190:193], v[22:25]
	v_mfma_f32_16x16x32_bf16 v[18:21], v[154:157], v[190:193], v[18:21]
	v_mfma_f32_16x16x32_bf16 v[6:9], v[138:141], v[206:209], v[6:9]
	v_mfma_f32_16x16x32_bf16 v[2:5], v[154:157], v[206:209], v[2:5]
	s_barrier
	s_add_i32 vcc_lo, vcc_lo, 2
	s_add_u32 s63, s63, 0x100
	s_addc_u32 s65, s65, 0
	s_cmp_gt_u32 vcc_lo, 13
	s_mov_b64 s[66:67], s[68:69]
	s_cbranch_scc0 .LBB0_617
	s_setprio 0
	s_and_b64 vcc, exec, s[52:53]
	s_cbranch_vccz .LBB0_620
	s_barrier
